# v5 plus GEMM K-loop LDS-DMA loads in saddr form (16 v_lshl_add_u64 removed) and 2-instruction cache-line prefetch in step_prep_hy
# speedup vs baseline: 1.0007x; 1.0007x over previous
; #define PG8_STAGE(bufoff, gbase, voff) do { _Pragma("unroll") for (int _i = 0; _i < 2; ++_i) \
;         __builtin_amdgcn_global_load_lds((const unsigned*)((const char*)(gbase) + (voff)[_i]), (PG8_LAS unsigned*)(lds + (bufoff) + ldsw + _i * 8192), 16, 0, 0); } while (0)
; #define PG8_LDA(dst, b, h) do { _Pragma("unroll") for (int m = 0; m < 4; ++m) _Pragma("unroll") for (int k = 0; k < 2; ++k) dst[m][k] = *(const PG8_LAS bf16x8*)(lds + PG8_SA(b, h) + aoff + m * 2048 + k * 1024); } while (0)
; #define PG8_LDB(dst, b, h) do { _Pragma("unroll") for (int n = 0; n < 2; ++n) _Pragma("unroll") for (int k = 0; k < 2; ++k) dst[n][k] = *(const PG8_LAS bf16x8*)(lds + PG8_SB(b, h) + boff + n * 2048 + k * 1024); } while (0)
; #define PG8_MMA(ai, bj, At, Bt) do { __builtin_amdgcn_s_setprio(1); _Pragma("unroll") for (int m = 0; m < 4; ++m) _Pragma("unroll") for (int n = 0; n < 2; ++n) _Pragma("unroll") for (int k = 0; k < 2; ++k) \
;         acc[ai][bj][m][n] = __builtin_amdgcn_mfma_f32_16x16x32_bf16(Bt[n][k], At[m][k], acc[ai][bj][m][n], 0, 0, 0); __builtin_amdgcn_s_setprio(0); } while (0)
; #define PG8_WAIT_V(n) asm volatile("s_waitcnt vmcnt(" #n ")" ::: "memory")
; #define PG8_WAIT_L(n) asm volatile("s_waitcnt lgkmcnt(" #n ")" ::: "memory")
; #define PG8_BAR __builtin_amdgcn_s_barrier()
; #define PG8_SCHED __builtin_amdgcn_sched_barrier(0)
; template <class Epi, class Sched, bool ALIGN_EPI = false, bool SP2 = false>
; __device__ __forceinline__ void gemm_phase(PG8_LAS unsigned char* lds, const Gemm g, const Sched& S, const Epi& E) {
;     ...
;             PG8_LDB(B0, 0, 0); PG8_LDB(B1, 0, 1); PG8_SCHED; PG8_LDA(At, 0, 0); PG8_STAGE(PG8_SA(1, 1), a1 + hstep, voffA);
;             PG8_WAIT_V(8); PG8_WAIT_L(0); PG8_BAR; PG8_MMA(0, 0, At, B0); PG8_MMA(0, 1, At, B1); PG8_BAR; PG8_SCHED;
;             PG8_LDA(At, 0, 1); PG8_STAGE(PG8_SB(0, 0), b2, voffB); PG8_STAGE(PG8_SB(0, 1), b2 + hstep, voffB); PG8_STAGE(PG8_SA(0, 0), a2, voffA);
;             PG8_WAIT_V(8); PG8_WAIT_L(0); PG8_BAR; PG8_MMA(1, 0, At, B0); PG8_MMA(1, 1, At, B1); PG8_BAR; PG8_SCHED;
.LBB0_137:
	s_add_i32 s25, s24, 2
	s_add_u32 s26, s44, 0x80
	s_addc_u32 s27, s45, 0
	s_add_i32 s52, 0, 0x10000
	s_cmp_eq_u32 s28, s24
	s_cselect_b32 s47, s87, s27
	s_cselect_b32 s46, s86, s26
	v_add_u32_e32 v0, s52, v228
	s_cselect_b32 s27, s7, s13
	s_cselect_b32 s26, s6, s12
	s_add_u32 s98, s26, 0x80
	s_addc_u32 s99, s27, 0
	s_add_i32 s24, 0, 0x14000
	s_waitcnt lgkmcnt(0)
	ds_read_b128 v[130:133], v0
	ds_read_b128 v[134:137], v0 offset:1024
	ds_read_b128 v[138:141], v0 offset:2048
	ds_read_b128 v[142:145], v0 offset:3072
	v_add_u32_e32 v0, s24, v228
	ds_read_b128 v[146:149], v0
	ds_read_b128 v[150:153], v0 offset:1024
	ds_read_b128 v[154:157], v0 offset:2048
	ds_read_b128 v[158:161], v0 offset:3072
	s_add_i32 m0, s37, 0xc000
	ds_read_b128 v[162:165], v230
	ds_read_b128 v[166:169], v230 offset:1024
	ds_read_b128 v[170:173], v230 offset:2048
	ds_read_b128 v[174:177], v230 offset:3072
	ds_read_b128 v[178:181], v230 offset:4096
	ds_read_b128 v[196:199], v230 offset:5120
	ds_read_b128 v[200:203], v230 offset:6144
	ds_read_b128 v[204:207], v230 offset:7168
	global_load_lds_dwordx4 v194, s[44:45]
	s_add_i32 m0, s37, 0xe000
	s_nop 0
	global_load_lds_dwordx4 v192, s[44:45]
	s_waitcnt vmcnt(8)
	s_waitcnt lgkmcnt(0)
	s_barrier
	s_setprio 1
	s_waitcnt lgkmcnt(0)
	v_mfma_f32_16x16x32_bf16 v[126:129], v[130:133], v[162:165], v[126:129]
	v_mfma_f32_16x16x32_bf16 v[122:125], v[138:141], v[162:165], v[122:125]
	v_mfma_f32_16x16x32_bf16 v[110:113], v[130:133], v[170:173], v[110:113]
	v_mfma_f32_16x16x32_bf16 v[106:109], v[138:141], v[170:173], v[106:109]
	v_mfma_f32_16x16x32_bf16 v[94:97], v[130:133], v[178:181], v[94:97]
	v_mfma_f32_16x16x32_bf16 v[90:93], v[138:141], v[178:181], v[90:93]
	v_mfma_f32_16x16x32_bf16 v[78:81], v[130:133], v[200:203], v[78:81]
	v_mfma_f32_16x16x32_bf16 v[74:77], v[138:141], v[200:203], v[74:77]
	v_mfma_f32_16x16x32_bf16 v[126:129], v[134:137], v[166:169], v[126:129]
	v_mfma_f32_16x16x32_bf16 v[122:125], v[142:145], v[166:169], v[122:125]
	v_mfma_f32_16x16x32_bf16 v[110:113], v[134:137], v[174:177], v[110:113]
	v_mfma_f32_16x16x32_bf16 v[106:109], v[142:145], v[174:177], v[106:109]
	v_mfma_f32_16x16x32_bf16 v[94:97], v[134:137], v[196:199], v[94:97]
	v_mfma_f32_16x16x32_bf16 v[90:93], v[142:145], v[196:199], v[90:93]
	v_mfma_f32_16x16x32_bf16 v[78:81], v[134:137], v[204:207], v[78:81]
	v_mfma_f32_16x16x32_bf16 v[74:77], v[142:145], v[204:207], v[74:77]
	s_setprio 0
	s_setprio 1
	v_mfma_f32_16x16x32_bf16 v[118:121], v[146:149], v[162:165], v[118:121]
	v_mfma_f32_16x16x32_bf16 v[114:117], v[154:157], v[162:165], v[114:117]
	v_mfma_f32_16x16x32_bf16 v[102:105], v[146:149], v[170:173], v[102:105]
	v_mfma_f32_16x16x32_bf16 v[98:101], v[154:157], v[170:173], v[98:101]
	v_mfma_f32_16x16x32_bf16 v[86:89], v[146:149], v[178:181], v[86:89]
	v_mfma_f32_16x16x32_bf16 v[82:85], v[154:157], v[178:181], v[82:85]
	v_mfma_f32_16x16x32_bf16 v[70:73], v[146:149], v[200:203], v[70:73]
	v_mfma_f32_16x16x32_bf16 v[66:69], v[154:157], v[200:203], v[66:69]
	v_mfma_f32_16x16x32_bf16 v[118:121], v[150:153], v[166:169], v[118:121]
	v_mfma_f32_16x16x32_bf16 v[114:117], v[158:161], v[166:169], v[114:117]
	v_mfma_f32_16x16x32_bf16 v[102:105], v[150:153], v[174:177], v[102:105]
	v_mfma_f32_16x16x32_bf16 v[98:101], v[158:161], v[174:177], v[98:101]
	v_mfma_f32_16x16x32_bf16 v[86:89], v[150:153], v[196:199], v[86:89]
	v_mfma_f32_16x16x32_bf16 v[82:85], v[158:161], v[196:199], v[82:85]
	v_mfma_f32_16x16x32_bf16 v[70:73], v[150:153], v[204:207], v[70:73]
	v_mfma_f32_16x16x32_bf16 v[66:69], v[158:161], v[204:207], v[66:69]
	s_setprio 0
	s_barrier
	s_add_i32 s52, s52, s36
	s_mov_b32 m0, s52
	ds_read_b128 v[162:165], v230 offset:16384
	ds_read_b128 v[166:169], v230 offset:17408
	ds_read_b128 v[170:173], v230 offset:18432
	ds_read_b128 v[174:177], v230 offset:19456
	ds_read_b128 v[178:181], v230 offset:20480
	ds_read_b128 v[196:199], v230 offset:21504
	ds_read_b128 v[200:203], v230 offset:22528
	ds_read_b128 v[204:207], v230 offset:23552
	global_load_lds_dwordx4 v186, s[26:27]
	s_add_i32 m0, s52, 0x2000
	s_add_i32 s24, s24, s36
	global_load_lds_dwordx4 v190, s[26:27]
	s_add_u32 s26, s26, s60
	s_addc_u32 s27, s27, 0
	s_mov_b32 m0, s24
	s_nop 0
	global_load_lds_dwordx4 v186, s[26:27]
	s_add_i32 m0, s24, 0x2000
	s_nop 0
	global_load_lds_dwordx4 v190, s[26:27]
	s_mov_b32 m0, s37
	s_nop 0
	global_load_lds_dwordx4 v184, s[46:47]
	s_mov_b32 m0, s62
	s_nop 0
	global_load_lds_dwordx4 v188, s[46:47]
	s_waitcnt vmcnt(8)
	s_waitcnt lgkmcnt(0)
	s_barrier
	s_setprio 1
	s_waitcnt lgkmcnt(0)
	v_mfma_f32_16x16x32_bf16 v[62:65], v[130:133], v[162:165], v[62:65]
	v_mfma_f32_16x16x32_bf16 v[58:61], v[138:141], v[162:165], v[58:61]
	v_mfma_f32_16x16x32_bf16 v[46:49], v[130:133], v[170:173], v[46:49]
	v_mfma_f32_16x16x32_bf16 v[42:45], v[138:141], v[170:173], v[42:45]
	v_mfma_f32_16x16x32_bf16 v[30:33], v[130:133], v[178:181], v[30:33]
	v_mfma_f32_16x16x32_bf16 v[26:29], v[138:141], v[178:181], v[26:29]
	v_mfma_f32_16x16x32_bf16 v[14:17], v[130:133], v[200:203], v[14:17]
	v_mfma_f32_16x16x32_bf16 v[10:13], v[138:141], v[200:203], v[10:13]
	v_mfma_f32_16x16x32_bf16 v[62:65], v[134:137], v[166:169], v[62:65]
	v_mfma_f32_16x16x32_bf16 v[58:61], v[142:145], v[166:169], v[58:61]
	v_mfma_f32_16x16x32_bf16 v[46:49], v[134:137], v[174:177], v[46:49]
	v_mfma_f32_16x16x32_bf16 v[42:45], v[142:145], v[174:177], v[42:45]
	v_mfma_f32_16x16x32_bf16 v[30:33], v[134:137], v[196:199], v[30:33]
	v_mfma_f32_16x16x32_bf16 v[26:29], v[142:145], v[196:199], v[26:29]
	v_mfma_f32_16x16x32_bf16 v[14:17], v[134:137], v[204:207], v[14:17]
	v_mfma_f32_16x16x32_bf16 v[10:13], v[142:145], v[204:207], v[10:13]
	s_setprio 0
	s_setprio 1
	v_mfma_f32_16x16x32_bf16 v[54:57], v[146:149], v[162:165], v[54:57]
	v_mfma_f32_16x16x32_bf16 v[50:53], v[154:157], v[162:165], v[50:53]
	v_mfma_f32_16x16x32_bf16 v[38:41], v[146:149], v[170:173], v[38:41]
	v_mfma_f32_16x16x32_bf16 v[34:37], v[154:157], v[170:173], v[34:37]
	v_mfma_f32_16x16x32_bf16 v[22:25], v[146:149], v[178:181], v[22:25]
	v_mfma_f32_16x16x32_bf16 v[18:21], v[154:157], v[178:181], v[18:21]
	v_mfma_f32_16x16x32_bf16 v[6:9], v[146:149], v[200:203], v[6:9]
	v_mfma_f32_16x16x32_bf16 v[2:5], v[154:157], v[200:203], v[2:5]
	v_mfma_f32_16x16x32_bf16 v[54:57], v[150:153], v[166:169], v[54:57]
	v_mfma_f32_16x16x32_bf16 v[50:53], v[158:161], v[166:169], v[50:53]
	v_mfma_f32_16x16x32_bf16 v[38:41], v[150:153], v[174:177], v[38:41]
	v_mfma_f32_16x16x32_bf16 v[34:37], v[158:161], v[174:177], v[34:37]
	v_mfma_f32_16x16x32_bf16 v[22:25], v[150:153], v[196:199], v[22:25]
	v_mfma_f32_16x16x32_bf16 v[18:21], v[158:161], v[196:199], v[18:21]
	v_mfma_f32_16x16x32_bf16 v[6:9], v[150:153], v[204:207], v[6:9]
	v_mfma_f32_16x16x32_bf16 v[2:5], v[158:161], v[204:207], v[2:5]
	s_setprio 0
	s_barrier
; #define PG8_STAGE(bufoff, gbase, voff) do { _Pragma("unroll") for (int _i = 0; _i < 2; ++_i) \
;         __builtin_amdgcn_global_load_lds((const unsigned*)((const char*)(gbase) + (voff)[_i]), (PG8_LAS unsigned*)(lds + (bufoff) + ldsw + _i * 8192), 16, 0, 0); } while (0)
; #define PG8_LDA(dst, b, h) do { _Pragma("unroll") for (int m = 0; m < 4; ++m) _Pragma("unroll") for (int k = 0; k < 2; ++k) dst[m][k] = *(const PG8_LAS bf16x8*)(lds + PG8_SA(b, h) + aoff + m * 2048 + k * 1024); } while (0)
; #define PG8_LDB(dst, b, h) do { _Pragma("unroll") for (int n = 0; n < 2; ++n) _Pragma("unroll") for (int k = 0; k < 2; ++k) dst[n][k] = *(const PG8_LAS bf16x8*)(lds + PG8_SB(b, h) + boff + n * 2048 + k * 1024); } while (0)
; #define PG8_MMA(ai, bj, At, Bt) do { __builtin_amdgcn_s_setprio(1); _Pragma("unroll") for (int m = 0; m < 4; ++m) _Pragma("unroll") for (int n = 0; n < 2; ++n) _Pragma("unroll") for (int k = 0; k < 2; ++k) \
;         acc[ai][bj][m][n] = __builtin_amdgcn_mfma_f32_16x16x32_bf16(Bt[n][k], At[m][k], acc[ai][bj][m][n], 0, 0, 0); __builtin_amdgcn_s_setprio(0); } while (0)
; #define PG8_WAIT_V(n) asm volatile("s_waitcnt vmcnt(" #n ")" ::: "memory")
; #define PG8_WAIT_L(n) asm volatile("s_waitcnt lgkmcnt(" #n ")" ::: "memory")
; #define PG8_BAR __builtin_amdgcn_s_barrier()
; #define PG8_SCHED __builtin_amdgcn_sched_barrier(0)
; template <class Epi, class Sched, bool ALIGN_EPI = false, bool SP2 = false>
; __device__ __forceinline__ void gemm_phase(PG8_LAS unsigned char* lds, const Gemm g, const Sched& S, const Epi& E) {
;     ...
;             PG8_LDB(B0, 1, 0); PG8_LDB(B1, 1, 1); PG8_SCHED; PG8_LDA(At, 1, 0); PG8_STAGE(PG8_SA(0, 1), a2 + hstep, voffA);
;             PG8_WAIT_V(8); PG8_WAIT_L(0); PG8_BAR; PG8_MMA(0, 0, At, B0); PG8_MMA(0, 1, At, B1); PG8_BAR; PG8_SCHED;
;             PG8_LDA(At, 1, 1); PG8_STAGE(PG8_SB(1, 0), b3, voffB); PG8_STAGE(PG8_SB(1, 1), b3 + hstep, voffB); PG8_STAGE(PG8_SA(1, 0), a3, voffA);
;             PG8_WAIT_V(8); PG8_WAIT_L(0); PG8_BAR; PG8_MMA(1, 0, At, B0); PG8_MMA(1, 1, At, B1); PG8_BAR; PG8_SCHED;
	s_add_i32 s24, 0, 0x18000
	v_add_u32_e32 v0, s24, v228
	s_add_i32 s52, 0, 0x1c000
	ds_read_b128 v[130:133], v0
	ds_read_b128 v[134:137], v0 offset:1024
	ds_read_b128 v[138:141], v0 offset:2048
	ds_read_b128 v[142:145], v0 offset:3072
	v_add_u32_e32 v0, s52, v228
	ds_read_b128 v[146:149], v0
	ds_read_b128 v[150:153], v0 offset:1024
	ds_read_b128 v[154:157], v0 offset:2048
	ds_read_b128 v[158:161], v0 offset:3072
	s_add_u32 s26, s46, s60
	s_addc_u32 s27, s47, 0
	s_mov_b32 m0, s88
	ds_read_b128 v[162:165], v230 offset:32768
	ds_read_b128 v[166:169], v230 offset:33792
	ds_read_b128 v[170:173], v230 offset:34816
	ds_read_b128 v[174:177], v230 offset:35840
	ds_read_b128 v[178:181], v230 offset:36864
	ds_read_b128 v[196:199], v230 offset:37888
	ds_read_b128 v[200:203], v230 offset:38912
	ds_read_b128 v[204:207], v230 offset:39936
	global_load_lds_dwordx4 v184, s[26:27]
	s_mov_b32 m0, s90
	s_nop 0
	global_load_lds_dwordx4 v188, s[26:27]
	s_waitcnt vmcnt(8)
	s_waitcnt lgkmcnt(0)
	s_barrier
	s_setprio 1
	s_waitcnt lgkmcnt(0)
	v_mfma_f32_16x16x32_bf16 v[126:129], v[130:133], v[162:165], v[126:129]
	v_mfma_f32_16x16x32_bf16 v[122:125], v[138:141], v[162:165], v[122:125]
	v_mfma_f32_16x16x32_bf16 v[110:113], v[130:133], v[170:173], v[110:113]
	v_mfma_f32_16x16x32_bf16 v[106:109], v[138:141], v[170:173], v[106:109]
	v_mfma_f32_16x16x32_bf16 v[94:97], v[130:133], v[178:181], v[94:97]
	v_mfma_f32_16x16x32_bf16 v[90:93], v[138:141], v[178:181], v[90:93]
	v_mfma_f32_16x16x32_bf16 v[78:81], v[130:133], v[200:203], v[78:81]
	v_mfma_f32_16x16x32_bf16 v[74:77], v[138:141], v[200:203], v[74:77]
	v_mfma_f32_16x16x32_bf16 v[126:129], v[134:137], v[166:169], v[126:129]
	v_mfma_f32_16x16x32_bf16 v[122:125], v[142:145], v[166:169], v[122:125]
	v_mfma_f32_16x16x32_bf16 v[110:113], v[134:137], v[174:177], v[110:113]
	v_mfma_f32_16x16x32_bf16 v[106:109], v[142:145], v[174:177], v[106:109]
	v_mfma_f32_16x16x32_bf16 v[94:97], v[134:137], v[196:199], v[94:97]
	v_mfma_f32_16x16x32_bf16 v[90:93], v[142:145], v[196:199], v[90:93]
	v_mfma_f32_16x16x32_bf16 v[78:81], v[134:137], v[204:207], v[78:81]
	v_mfma_f32_16x16x32_bf16 v[74:77], v[142:145], v[204:207], v[74:77]
	s_setprio 0
	s_setprio 1
	v_mfma_f32_16x16x32_bf16 v[118:121], v[146:149], v[162:165], v[118:121]
	v_mfma_f32_16x16x32_bf16 v[114:117], v[154:157], v[162:165], v[114:117]
	v_mfma_f32_16x16x32_bf16 v[102:105], v[146:149], v[170:173], v[102:105]
	v_mfma_f32_16x16x32_bf16 v[98:101], v[154:157], v[170:173], v[98:101]
	v_mfma_f32_16x16x32_bf16 v[86:89], v[146:149], v[178:181], v[86:89]
	v_mfma_f32_16x16x32_bf16 v[82:85], v[154:157], v[178:181], v[82:85]
	v_mfma_f32_16x16x32_bf16 v[70:73], v[146:149], v[200:203], v[70:73]
	v_mfma_f32_16x16x32_bf16 v[66:69], v[154:157], v[200:203], v[66:69]
	v_mfma_f32_16x16x32_bf16 v[118:121], v[150:153], v[166:169], v[118:121]
	v_mfma_f32_16x16x32_bf16 v[114:117], v[158:161], v[166:169], v[114:117]
	v_mfma_f32_16x16x32_bf16 v[102:105], v[150:153], v[174:177], v[102:105]
	v_mfma_f32_16x16x32_bf16 v[98:101], v[158:161], v[174:177], v[98:101]
	v_mfma_f32_16x16x32_bf16 v[86:89], v[150:153], v[196:199], v[86:89]
	v_mfma_f32_16x16x32_bf16 v[82:85], v[158:161], v[196:199], v[82:85]
	v_mfma_f32_16x16x32_bf16 v[70:73], v[150:153], v[204:207], v[70:73]
	v_mfma_f32_16x16x32_bf16 v[66:69], v[158:161], v[204:207], v[66:69]
	s_setprio 0
	s_barrier
	s_add_i32 s24, s24, s36
	s_mov_b32 m0, s24
	ds_read_b128 v[162:165], v230 offset:49152
	ds_read_b128 v[166:169], v230 offset:50176
	ds_read_b128 v[170:173], v230 offset:51200
	ds_read_b128 v[174:177], v230 offset:52224
	ds_read_b128 v[178:181], v230 offset:53248
	ds_read_b128 v[196:199], v230 offset:54272
	ds_read_b128 v[200:203], v230 offset:55296
	ds_read_b128 v[204:207], v230 offset:56320
	global_load_lds_dwordx4 v186, s[98:99]
	s_add_i32 m0, s24, 0x2000
	s_add_i32 s24, s52, s36
	global_load_lds_dwordx4 v190, s[98:99]
	s_add_u32 s98, s98, s60
	s_addc_u32 s99, s99, 0
	s_mov_b32 m0, s24
	s_nop 0
	global_load_lds_dwordx4 v186, s[98:99]
	s_add_i32 m0, s24, 0x2000
	s_nop 0
	global_load_lds_dwordx4 v190, s[98:99]
	s_add_u32 s98, s46, 0x80
	s_addc_u32 s99, s47, 0
	s_mov_b32 m0, s72
	s_nop 0
	global_load_lds_dwordx4 v184, s[98:99]
	s_mov_b32 m0, s73
	s_nop 0
	global_load_lds_dwordx4 v188, s[98:99]
	s_waitcnt vmcnt(8)
	s_waitcnt lgkmcnt(0)
	s_barrier
	s_setprio 1
	s_waitcnt lgkmcnt(0)
	v_mfma_f32_16x16x32_bf16 v[62:65], v[130:133], v[162:165], v[62:65]
	v_mfma_f32_16x16x32_bf16 v[58:61], v[138:141], v[162:165], v[58:61]
	v_mfma_f32_16x16x32_bf16 v[46:49], v[130:133], v[170:173], v[46:49]
	v_mfma_f32_16x16x32_bf16 v[42:45], v[138:141], v[170:173], v[42:45]
	v_mfma_f32_16x16x32_bf16 v[30:33], v[130:133], v[178:181], v[30:33]
	v_mfma_f32_16x16x32_bf16 v[26:29], v[138:141], v[178:181], v[26:29]
	v_mfma_f32_16x16x32_bf16 v[14:17], v[130:133], v[200:203], v[14:17]
	v_mfma_f32_16x16x32_bf16 v[10:13], v[138:141], v[200:203], v[10:13]
	v_mfma_f32_16x16x32_bf16 v[62:65], v[134:137], v[166:169], v[62:65]
	v_mfma_f32_16x16x32_bf16 v[58:61], v[142:145], v[166:169], v[58:61]
	v_mfma_f32_16x16x32_bf16 v[46:49], v[134:137], v[174:177], v[46:49]
	v_mfma_f32_16x16x32_bf16 v[42:45], v[142:145], v[174:177], v[42:45]
	v_mfma_f32_16x16x32_bf16 v[30:33], v[134:137], v[196:199], v[30:33]
	v_mfma_f32_16x16x32_bf16 v[26:29], v[142:145], v[196:199], v[26:29]
	v_mfma_f32_16x16x32_bf16 v[14:17], v[134:137], v[204:207], v[14:17]
	v_mfma_f32_16x16x32_bf16 v[10:13], v[142:145], v[204:207], v[10:13]
	s_setprio 0
	s_setprio 1
	v_mfma_f32_16x16x32_bf16 v[54:57], v[146:149], v[162:165], v[54:57]
	v_mfma_f32_16x16x32_bf16 v[50:53], v[154:157], v[162:165], v[50:53]
	v_mfma_f32_16x16x32_bf16 v[38:41], v[146:149], v[170:173], v[38:41]
	v_mfma_f32_16x16x32_bf16 v[34:37], v[154:157], v[170:173], v[34:37]
	v_mfma_f32_16x16x32_bf16 v[22:25], v[146:149], v[178:181], v[22:25]
	v_mfma_f32_16x16x32_bf16 v[18:21], v[154:157], v[178:181], v[18:21]
	v_mfma_f32_16x16x32_bf16 v[6:9], v[146:149], v[200:203], v[6:9]
	v_mfma_f32_16x16x32_bf16 v[2:5], v[154:157], v[200:203], v[2:5]
	v_mfma_f32_16x16x32_bf16 v[54:57], v[150:153], v[166:169], v[54:57]
	v_mfma_f32_16x16x32_bf16 v[50:53], v[158:161], v[166:169], v[50:53]
	v_mfma_f32_16x16x32_bf16 v[38:41], v[150:153], v[174:177], v[38:41]
	v_mfma_f32_16x16x32_bf16 v[34:37], v[158:161], v[174:177], v[34:37]
	v_mfma_f32_16x16x32_bf16 v[22:25], v[150:153], v[196:199], v[22:25]
	v_mfma_f32_16x16x32_bf16 v[18:21], v[158:161], v[196:199], v[18:21]
	v_mfma_f32_16x16x32_bf16 v[6:9], v[150:153], v[204:207], v[6:9]
	v_mfma_f32_16x16x32_bf16 v[2:5], v[158:161], v[204:207], v[2:5]
	s_setprio 0
	s_barrier
	s_add_u32 s12, s12, 0x100
	s_addc_u32 s13, s13, 0
	s_add_u32 s44, s44, 0x100
	s_addc_u32 s45, s45, 0
	s_cmp_ge_u32 s25, s91
	s_mov_b32 s24, s25
	s_cbranch_scc0 .LBB0_137
	s_and_b64 vcc, exec, s[84:85]
	s_cbranch_vccz .LBB0_140
	s_barrier

; __device__ __forceinline__ int lbid() { int b = (int)blockIdx.x; asm volatile("" : "+s"(b)); return b; }
; __device__ __forceinline__ void step_prep_hy(const AV& a, LAS unsigned char* lds, int c, int layer) {
;     ...
;     for (int it = lbid() * NWAVES + wave; it < (CH / 16) * 4; it += gridDim.x * NWAVES) {
;         const int cbk = it & 3, tg = it >> 2, t0 = tg * 16, ch = cbk * 128 + 2 * lane;
;         const int pos0 = t0 & (ck.L - 1);
;         float w[3][3][2], bb[3][2];
; #pragma unroll
;         for (int ar = 0; ar < 3; ++ar) {
; #pragma unroll
;             for (int j = 0; j < 3; ++j) { const f32x2 v = *(const f32x2*)(cw + j * 1536 + ar * 512 + ch); w[ar][j][0] = v.x; w[ar][j][1] = v.y; }
;             const f32x2 v = *(const f32x2*)(cb + ar * 512 + ch); bb[ar][0] = v.x; bb[ar][1] = v.y; }
;         const bf16* r0 = U + (size_t)t0 * UP + ch;
;         unsigned pv[3], cv[3], nv[3];
; #pragma unroll
;         for (int ar = 0; ar < 3; ++ar) { pv[ar] = pos0 > 0 ? *(const unsigned*)(r0 - UP + ar * 512) : 0u; cv[ar] = *(const unsigned*)(r0 + ar * 512); }
; #pragma unroll 4
;         for (int t = 0; t < 16; ++t) {
;             const bf16* rt = r0 + (size_t)t * UP; const bool last = (pos0 + t + 1 >= ck.L);
; #pragma unroll
;             for (int ar = 0; ar < 3; ++ar) nv[ar] = last ? 0u : *(const unsigned*)(rt + UP + ar * 512);
.LBB0_351:
	v_and_b32_e32 v60, 3, v52
	v_lshl_or_b32 v33, v60, 7, v53
	v_lshlrev_b32_e32 v0, 2, v33
	v_lshl_add_u64 v[20:21], s[6:7], 0, v[0:1]
	v_add_co_u32_e32 v18, vcc, 0x1000, v20
	s_movk_i32 s12, 0x2000
	s_nop 0
	v_addc_co_u32_e32 v19, vcc, 0, v21, vcc
	v_add_co_u32_e32 v16, vcc, 0x3000, v20
	v_lshl_add_u64 v[26:27], s[42:43], 0, v[0:1]
	s_nop 0
	v_addc_co_u32_e32 v17, vcc, 0, v21, vcc
	v_add_co_u32_e32 v22, vcc, s12, v20
	flat_load_dwordx2 v[4:5], v[20:21]
	flat_load_dwordx2 v[6:7], v[20:21] offset:2048
	v_addc_co_u32_e32 v23, vcc, 0, v21, vcc
	flat_load_dwordx2 v[8:9], v[26:27]
	flat_load_dwordx2 v[10:11], v[26:27] offset:2048
	flat_load_dwordx2 v[12:13], v[18:19] offset:2048
	flat_load_dwordx2 v[14:15], v[16:17]
	s_nop 0
	flat_load_dwordx2 v[16:17], v[16:17] offset:2048
	s_nop 0
	flat_load_dwordx2 v[18:19], v[18:19]
	v_add_co_u32_e32 v24, vcc, s77, v20
	s_movk_i32 s12, 0x1000
	s_nop 0
	v_addc_co_u32_e32 v25, vcc, 0, v21, vcc
	v_add_co_u32_e32 v26, vcc, s12, v26
	flat_load_dwordx2 v[20:21], v[22:23]
	s_nop 0
	flat_load_dwordx2 v[22:23], v[22:23] offset:2048
	s_nop 0
	flat_load_dwordx2 v[24:25], v[24:25]
	v_addc_co_u32_e32 v27, vcc, 0, v27, vcc
	flat_load_dwordx2 v[28:29], v[26:27]
	v_lshlrev_b32_e32 v0, 2, v52
	v_and_b32_e32 v26, -16, v0
	v_mov_b64_e32 v[30:31], s[2:3]
	v_bitop3_b32 v32, v0, s15, -16 bitop3:0x80
	v_mad_i64_i32 v[30:31], s[12:13], v26, s60, v[30:31]
	v_lshlrev_b32_e32 v0, 1, v33
	v_lshl_add_u64 v[30:31], v[30:31], 0, v[0:1]
	v_and_b32_e32 v100, 63, v210
	v_lshrrev_b32_e32 v101, 2, v100
	v_mul_u32_u24_e32 v101, 0x2a00, v101
	v_and_b32_e32 v102, 3, v100
	v_lshlrev_b32_e32 v102, 10, v102
	v_add_u32_e32 v101, v101, v102
	v_lshlrev_b32_e32 v102, 2, v100
	v_sub_u32_e32 v101, v101, v102
	v_add_co_u32_e32 v102, vcc, v30, v101
	s_nop 1
	v_addc_co_u32_e32 v103, vcc, 0, v31, vcc
	global_load_dword v104, v[102:103], off
	global_load_dword v105, v[102:103], off offset:128
	v_mov_b32_e32 v62, 0
	v_cmp_lt_i32_e64 s[40:41], 0, v32
	v_mov_b32_e32 v63, 0
	s_and_saveexec_b64 s[12:13], s[40:41]
	s_cbranch_execz .LBB0_353
	v_add_co_u32_e32 v34, vcc, 0xffffd600, v30
	s_nop 1
	v_addc_co_u32_e32 v35, vcc, -1, v31, vcc
	flat_load_dword v63, v[34:35]
